# MIX queue restructure: MIX-1 runs only delta_pre; s5_prompt/s5_block/lru_pass1 items moved into the MIX-2 queue beside the delta_seq chains, with release/acquire completion counters gating GLU and lru
# speedup vs baseline: 1.1396x; 1.0187x over previous
_Z4mega1P:
	s_mov_b32 s100, 0
	s_mov_b32 s101, 0
	s_load_dwordx16 s[64:79], s[0:1], 0x0
	s_load_dwordx16 s[4:19], s[0:1], 0x40
	s_load_dwordx16 s[36:51], s[0:1], 0x140
	s_mov_b32 s82, s2
	s_add_u32 s2, s0, 0x180
	s_addc_u32 s3, s1, 0
	s_waitcnt lgkmcnt(0)
	v_writelane_b32 v252, s4, 0
	s_load_dword s33, s[0:1], 0x180
	v_writelane_b32 v253, s2, 0
	v_writelane_b32 v252, s5, 1
	v_writelane_b32 v252, s6, 2
	v_writelane_b32 v252, s7, 3
	v_writelane_b32 v252, s8, 4
	v_writelane_b32 v252, s9, 5
	v_writelane_b32 v252, s10, 6
	v_writelane_b32 v252, s11, 7
	v_writelane_b32 v252, s12, 8
	v_writelane_b32 v252, s13, 9
	v_writelane_b32 v252, s14, 10
	v_writelane_b32 v252, s15, 11
	v_writelane_b32 v252, s16, 12
	v_writelane_b32 v252, s17, 13
	v_writelane_b32 v252, s18, 14
	v_writelane_b32 v252, s19, 15
	s_load_dwordx16 s[4:19], s[0:1], 0x80
	v_writelane_b32 v253, s3, 1
	v_and_b32_e32 v216, 0x3ff, v0
	v_and_b32_e32 v0, 0x3fffffff, v0
	s_mov_b32 s95, 0
	s_waitcnt lgkmcnt(0)
	v_writelane_b32 v252, s4, 16
	v_mov_b32_e32 v201, 0
	v_mov_b32_e32 v217, 0x358637bd
	v_writelane_b32 v252, s5, 17
	v_writelane_b32 v252, s6, 18
	v_writelane_b32 v252, s7, 19
	v_writelane_b32 v252, s8, 20
	v_writelane_b32 v252, s9, 21
	v_writelane_b32 v252, s10, 22
	v_writelane_b32 v252, s11, 23
	v_writelane_b32 v252, s12, 24
	v_writelane_b32 v252, s13, 25
	v_writelane_b32 v252, s14, 26
	v_writelane_b32 v252, s15, 27
	v_writelane_b32 v252, s16, 28
	v_writelane_b32 v252, s17, 29
	v_writelane_b32 v252, s18, 30
	v_writelane_b32 v252, s19, 31
	s_load_dwordx16 s[4:19], s[0:1], 0xc0
	s_mov_b64 s[96:97], 0x80
	v_mov_b32_e32 v224, 0x3c0881c4
	v_mov_b32_e32 v226, 0xbab64f3b
	s_mov_b32 s24, 0x3f200000
	s_waitcnt lgkmcnt(0)
	v_writelane_b32 v252, s4, 32
	v_mov_b32_e32 v228, 0x3ca908c9
	v_mov_b32_e32 v229, 0x3ecc95a3
	v_writelane_b32 v252, s5, 33
	v_writelane_b32 v252, s6, 34
	v_writelane_b32 v252, s7, 35
	v_writelane_b32 v252, s8, 36
	v_writelane_b32 v252, s9, 37
	v_writelane_b32 v252, s10, 38
	v_writelane_b32 v252, s11, 39
	v_writelane_b32 v252, s12, 40
	v_writelane_b32 v252, s13, 41
	v_writelane_b32 v252, s14, 42
	v_writelane_b32 v252, s15, 43
	v_writelane_b32 v252, s16, 44
	v_writelane_b32 v252, s17, 45
	v_writelane_b32 v252, s18, 46
	v_writelane_b32 v252, s19, 47
	s_load_dwordx16 s[4:19], s[0:1], 0x100
	s_add_u32 s0, s50, 0x4490000
	s_addc_u32 s1, s51, 0
	v_writelane_b32 v253, s0, 2
	v_mov_b32_e32 v230, 0x3ab69700
	s_waitcnt lgkmcnt(0)
	v_writelane_b32 v252, s4, 48
	v_writelane_b32 v253, s1, 3
	s_add_u32 s0, s50, 0x7650000
	s_addc_u32 s1, s51, 0
	v_writelane_b32 v253, s0, 4
	v_writelane_b32 v252, s5, 49
	v_writelane_b32 v252, s6, 50
	v_writelane_b32 v253, s1, 5
	s_add_u32 s0, s50, 0x10000
	s_addc_u32 s1, s51, 0
	v_writelane_b32 v253, s0, 6
	s_add_u32 s28, s50, 0x9919000
	s_addc_u32 s29, s51, 0
	v_writelane_b32 v253, s1, 7
	s_lshl_b32 s0, s82, 2
	s_lshl_b32 s81, s33, 2
	v_writelane_b32 v253, s0, 8
	s_add_u32 s0, s50, 0x4f90000
	s_addc_u32 s1, s51, 0
	v_writelane_b32 v253, s0, 9
	v_writelane_b32 v252, s7, 51
	v_writelane_b32 v252, s8, 52
	v_writelane_b32 v253, s1, 10
	s_add_u32 s0, s50, 0x5510000
	s_addc_u32 s1, s51, 0
	v_writelane_b32 v253, s0, 11
	v_writelane_b32 v252, s9, 53
	v_writelane_b32 v252, s10, 54
	v_writelane_b32 v253, s1, 12
	s_add_u32 s0, s50, 0x5990000
	s_addc_u32 s1, s51, 0
	v_writelane_b32 v253, s0, 13
	v_writelane_b32 v252, s11, 55
	v_writelane_b32 v252, s12, 56
	v_writelane_b32 v253, s1, 14
	s_add_u32 s0, s50, 0x6190000
	v_writelane_b32 v253, s0, 15
	s_addc_u32 s0, s51, 0
	v_writelane_b32 v253, s0, 16
	s_add_u32 s0, s50, 0x6390000
	s_addc_u32 s1, s51, 0
	v_writelane_b32 v253, s0, 17
	v_writelane_b32 v252, s13, 57
	v_writelane_b32 v252, s14, 58
	v_writelane_b32 v253, s1, 18
	s_add_u32 s0, s50, 0x6590000
	s_addc_u32 s1, s51, 0
	v_writelane_b32 v253, s0, 19
	v_writelane_b32 v252, s15, 59
	v_writelane_b32 v252, s16, 60
	v_writelane_b32 v253, s1, 20
	s_add_u32 s0, s50, 0x65d0000
	s_addc_u32 s1, s51, 0
	v_writelane_b32 v253, s0, 21
	v_writelane_b32 v252, s17, 61
	v_writelane_b32 v252, s18, 62
	v_writelane_b32 v253, s1, 22
	s_add_u32 s0, s50, 0x70d0000
	s_addc_u32 s1, s51, 0
	v_writelane_b32 v253, s0, 23
	s_add_i32 s2, s33, 0xbc5
	v_writelane_b32 v252, s19, 63
	v_writelane_b32 v253, s1, 24
	v_cmp_eq_u32_e64 s[0:1], 0, v0
	s_movk_i32 s18, 0x6420
	s_brev_b32 s19, -2
	v_writelane_b32 v253, s0, 25
	s_mov_b32 s25, 0x43000000
	s_mov_b32 s26, 0xf800000
	v_writelane_b32 v253, s1, 26
	s_ashr_i32 s0, s33, 3
	s_add_i32 s1, s33, 0x447
	s_add_u32 s4, s50, 0x9890000
	v_writelane_b32 v253, s0, 27
	s_addc_u32 s5, s51, 0
	v_writelane_b32 v253, s4, 28
	s_add_i32 s0, s33, 0x4d0
	s_add_u32 s3, s50, 0x11989000
	v_writelane_b32 v253, s5, 29
	v_cmp_eq_u32_e64 s[4:5], 0, v216
	v_mov_b32_e32 v231, 0x260
	s_mov_b32 s27, 0xc1880000
	v_writelane_b32 v253, s4, 30
	v_mov_b32_e32 v232, 1
	v_mov_b32_e32 v233, 0x7f800000
	v_writelane_b32 v253, s5, 31
	v_writelane_b32 v253, s3, 32
	s_addc_u32 s3, s51, 0
	v_writelane_b32 v253, s3, 33
	s_add_u32 s3, s48, 0x580c000
	v_writelane_b32 v253, s3, 34
	s_addc_u32 s3, s49, 0
	v_writelane_b32 v253, s3, 35
	s_add_u32 s3, s48, 0x590c000
	v_writelane_b32 v253, s3, 36
	s_addc_u32 s3, s49, 0
	s_add_u32 s6, s50, 0x10869000
	s_addc_u32 s7, s51, 0
	s_add_u32 s22, s50, 0x110f9000
	s_addc_u32 s23, s51, 0
	v_writelane_b32 v253, s3, 37
	s_add_u32 s3, s48, 0x5a4c000
	v_writelane_b32 v253, s3, 38
	s_addc_u32 s3, s49, 0
	v_writelane_b32 v253, s3, 39
	s_add_u32 s3, s48, 0x4548000
	v_writelane_b32 v253, s3, 40
	s_addc_u32 s3, s49, 0
	v_writelane_b32 v253, s3, 41
	s_add_u32 s3, s50, 0x400
	v_writelane_b32 v253, s3, 42
	s_addc_u32 s3, s51, 0
	v_writelane_b32 v253, s3, 43
	s_add_u32 s3, s48, 0x4524000
	v_writelane_b32 v253, s3, 44
	s_addc_u32 s3, s49, 0
	v_writelane_b32 v253, s3, 45
	s_add_u32 s3, s48, 0x4534000
	v_writelane_b32 v253, s3, 46
	s_addc_u32 s3, s49, 0
	v_writelane_b32 v253, s3, 47
	s_add_u32 s3, s48, 0x5b0c000
	v_writelane_b32 v253, s3, 48
	s_addc_u32 s3, s49, 0
	v_writelane_b32 v253, s3, 49
	s_add_u32 s3, s48, 0x4554000
	v_writelane_b32 v253, s3, 50
	s_addc_u32 s3, s49, 0
	s_add_u32 s4, s50, 0x9919c00
	v_writelane_b32 v253, s3, 51
	s_addc_u32 s5, s51, 0
	v_writelane_b32 v253, s4, 52
	v_not_b32_e32 v234, 63
	v_not_b32_e32 v235, 31
	v_writelane_b32 v253, s5, 53
	s_add_u32 s4, s50, 0xe629400
	s_addc_u32 s5, s51, 0
	v_writelane_b32 v253, s4, 54
	s_add_u32 s3, s48, 0x5a0c000
	v_mov_b32_e32 v236, 0x7fc00000
	v_writelane_b32 v253, s5, 55
	v_writelane_b32 v253, s3, 56
	s_addc_u32 s3, s49, 0
	v_writelane_b32 v253, s3, 57
	v_writelane_b32 v253, s64, 58
	s_cmp_lg_u64 s[68:69], 0
	s_cselect_b64 s[4:5], -1, 0
	v_writelane_b32 v254, s70, 0
	v_writelane_b32 v254, s71, 1
	v_writelane_b32 v254, s72, 2
	v_writelane_b32 v254, s73, 3
	v_writelane_b32 v254, s74, 4
	v_writelane_b32 v254, s75, 5
	v_writelane_b32 v254, s76, 6
	v_writelane_b32 v254, s77, 7
	v_writelane_b32 v254, s78, 8
	v_writelane_b32 v254, s79, 9
	v_writelane_b32 v254, s4, 10
	v_writelane_b32 v253, s65, 59
	v_writelane_b32 v253, s66, 60
	v_writelane_b32 v254, s5, 11
	s_add_u32 s4, s50, 0xe629000
	s_addc_u32 s5, s51, 0
	v_writelane_b32 v254, s4, 12
	s_add_u32 s3, s48, 0x45cc000
	v_writelane_b32 v253, s67, 61
	v_writelane_b32 v254, s5, 13
	v_writelane_b32 v254, s3, 14
	s_addc_u32 s3, s49, 0
	v_writelane_b32 v254, s3, 15
	s_add_u32 s3, s48, 0x4544000
	v_writelane_b32 v254, s3, 16
	s_addc_u32 s3, s49, 0
	v_writelane_b32 v254, s3, 17
	s_add_u32 s3, s48, 0x4400000
	v_writelane_b32 v254, s3, 18
	s_addc_u32 s3, s49, 0
	s_abs_i32 s93, s33
	v_cvt_f32_u32_e32 v0, s93
	s_sub_i32 s8, 0, s93
	s_abs_i32 s5, s82
	v_writelane_b32 v254, s3, 19
	v_rcp_iflag_f32_e32 v0, v0
	s_add_i32 s3, s33, 0x88f
	s_ashr_i32 s4, s82, 31
	v_writelane_b32 v253, s68, 62
	v_mul_f32_e32 v0, 0x4f7ffffe, v0
	v_cvt_u32_f32_e32 v0, v0
	v_readlane_b32 s52, v252, 0
	v_readlane_b32 s53, v252, 1
	v_writelane_b32 v253, s69, 63
	v_readfirstlane_b32 s9, v0
	s_mul_i32 s8, s8, s9
	s_mul_hi_u32 s8, s9, s8
	s_add_i32 s10, s9, s8
	s_mul_hi_u32 s8, s5, s10
	s_mul_i32 s8, s8, s93
	s_sub_i32 s5, s5, s8
	s_sub_i32 s8, s5, s93
	s_cmp_ge_u32 s5, s93
	s_cselect_b32 s5, s8, s5
	s_sub_i32 s8, s5, s93
	s_cmp_ge_u32 s5, s93
	s_cselect_b32 s5, s8, s5
	s_xor_b32 s5, s5, s4
	s_sub_i32 s4, s5, s4
	s_ashr_i32 s5, s4, 31
	s_and_b32 s5, s5, s33
	s_add_i32 s11, s5, s4
	s_cmpk_lt_i32 s11, 0x580
	s_cselect_b64 s[4:5], -1, 0
	v_writelane_b32 v254, s4, 20
	s_mov_b32 s75, 0x800000
	v_mbcnt_lo_u32_b32 v0, -1, 0
	v_writelane_b32 v254, s5, 21
	s_mul_hi_u32 s4, s10, 0x580
	s_mul_i32 s4, s4, s93
	s_sub_i32 s4, 0x580, s4
	s_sub_i32 s5, s4, s93
	s_cmp_ge_u32 s4, s93
	s_cselect_b32 s4, s5, s4
	s_sub_i32 s5, s4, s93
	s_cmp_ge_u32 s4, s93
	s_cselect_b32 s4, s5, s4
	s_sub_i32 s5, s82, s4
	s_ashr_i32 s8, s5, 31
	s_abs_i32 s5, s5
	s_mul_hi_u32 s9, s5, s10
	s_mul_i32 s9, s9, s93
	s_sub_i32 s5, s5, s9
	s_sub_i32 s9, s5, s93
	s_cmp_ge_u32 s5, s93
	s_cselect_b32 s5, s9, s5
	s_sub_i32 s9, s5, s93
	s_cmp_ge_u32 s5, s93
	s_cselect_b32 s5, s9, s5
	s_xor_b32 s5, s5, s8
	s_sub_i32 s5, s5, s8
	s_ashr_i32 s8, s5, 31
	s_and_b32 s8, s8, s33
	s_add_i32 s12, s8, s5
	s_cmpk_lt_i32 s12, 0x2c0
	s_cselect_b64 s[8:9], -1, 0
	s_addk_i32 s4, 0x2c0
	v_writelane_b32 v254, s8, 22
	s_ashr_i32 s5, s4, 31
	s_abs_i32 s4, s4
	v_writelane_b32 v254, s9, 23
	s_mul_hi_u32 s8, s4, s10
	s_mul_i32 s8, s8, s93
	s_sub_i32 s4, s4, s8
	s_sub_i32 s8, s4, s93
	s_cmp_ge_u32 s4, s93
	s_cselect_b32 s4, s8, s4
	s_sub_i32 s8, s4, s93
	s_cmp_ge_u32 s4, s93
	s_cselect_b32 s4, s8, s4
	s_xor_b32 s4, s4, s5
	s_sub_i32 s4, s4, s5
	s_sub_i32 s5, s82, s4
	s_ashr_i32 s8, s5, 31
	s_abs_i32 s5, s5
	s_mul_hi_u32 s9, s5, s10
	s_mul_i32 s9, s9, s93
	s_sub_i32 s5, s5, s9
	s_sub_i32 s9, s5, s93
	s_cmp_ge_u32 s5, s93
	s_cselect_b32 s5, s9, s5
	s_sub_i32 s9, s5, s93
	s_cmp_ge_u32 s5, s93
	s_cselect_b32 s5, s9, s5
	s_xor_b32 s5, s5, s8
	s_sub_i32 s5, s5, s8
	s_ashr_i32 s8, s5, 31
	s_and_b32 s8, s8, s33
	s_add_i32 s13, s8, s5
	s_cmpk_lt_i32 s13, 0x240
	s_cselect_b64 s[8:9], -1, 0
	s_addk_i32 s4, 0x240
	v_writelane_b32 v254, s8, 24
	s_ashr_i32 s5, s4, 31
	s_abs_i32 s4, s4
	v_writelane_b32 v254, s9, 25
	s_mul_hi_u32 s8, s4, s10
	s_mul_i32 s8, s8, s93
	s_sub_i32 s4, s4, s8
	s_sub_i32 s8, s4, s93
	s_cmp_ge_u32 s4, s93
	s_cselect_b32 s4, s8, s4
	s_sub_i32 s8, s4, s93
	s_cmp_ge_u32 s4, s93
	s_cselect_b32 s4, s8, s4
	s_xor_b32 s4, s4, s5
	s_sub_i32 s4, s4, s5
	s_sub_i32 s5, s82, s4
	s_ashr_i32 s8, s5, 31
	s_abs_i32 s5, s5
	s_mul_hi_u32 s9, s5, s10
	s_mul_i32 s9, s9, s93
	s_sub_i32 s5, s5, s9
	s_sub_i32 s9, s5, s93
	s_cmp_ge_u32 s5, s93
	s_cselect_b32 s5, s9, s5
	s_sub_i32 s9, s5, s93
	s_cmp_ge_u32 s5, s93
	s_cselect_b32 s5, s9, s5
	s_xor_b32 s5, s5, s8
	s_sub_i32 s5, s5, s8
	s_ashr_i32 s8, s5, 31
	s_and_b32 s8, s8, s33
	s_add_i32 s9, s8, s5
	s_cmpk_lt_i32 s9, 0x400
	s_cselect_b64 s[14:15], -1, 0
	s_addk_i32 s4, 0x400
	s_ashr_i32 s5, s4, 31
	s_abs_i32 s4, s4
	s_mul_hi_u32 s8, s4, s10
	s_mul_i32 s8, s8, s93
	s_sub_i32 s4, s4, s8
	s_sub_i32 s8, s4, s93
	s_cmp_ge_u32 s4, s93
	s_cselect_b32 s4, s8, s4
	s_sub_i32 s8, s4, s93
	s_cmp_ge_u32 s4, s93
	s_cselect_b32 s4, s8, s4
	s_xor_b32 s4, s4, s5
	s_sub_i32 s4, s4, s5
	s_abs_i32 s5, s2
	s_mul_hi_u32 s8, s5, s10
	v_writelane_b32 v254, s14, 26
	s_mul_i32 s8, s8, s93
	s_sub_i32 s5, s5, s8
	v_writelane_b32 v254, s15, 27
	v_writelane_b32 v254, s4, 28
	s_ashr_i32 s4, s2, 31
	s_sub_i32 s8, s5, s93
	s_cmp_ge_u32 s5, s93
	s_cselect_b32 s5, s8, s5
	s_sub_i32 s8, s5, s93
	s_cmp_ge_u32 s5, s93
	s_cselect_b32 s5, s8, s5
	s_xor_b32 s5, s5, s4
	s_sub_i32 s4, s4, s5
	s_add_i32 s2, s2, s4
	s_cmp_lt_i32 s82, s2
	v_writelane_b32 v254, s2, 29
	s_cselect_b64 s[4:5], -1, 0
	v_writelane_b32 v254, s4, 30
	s_ashr_i32 s2, s1, 31
	v_mbcnt_hi_u32_b32 v218, -1, v0
	v_writelane_b32 v254, s5, 31
	s_abs_i32 s4, s1
	s_mul_hi_u32 s5, s4, s10
	s_mul_i32 s5, s5, s93
	s_sub_i32 s4, s4, s5
	s_sub_i32 s5, s4, s93
	s_cmp_ge_u32 s4, s93
	s_cselect_b32 s4, s5, s4
	s_sub_i32 s5, s4, s93
	s_cmp_ge_u32 s4, s93
	s_cselect_b32 s4, s5, s4
	s_xor_b32 s4, s4, s2
	s_sub_i32 s2, s2, s4
	s_add_i32 s1, s1, s2
	s_cmp_lt_i32 s82, s1
	v_writelane_b32 v254, s1, 32
	s_cselect_b64 s[4:5], -1, 0
	v_writelane_b32 v254, s4, 33
	s_abs_i32 s2, s0
	s_ashr_i32 s1, s0, 31
	v_writelane_b32 v254, s5, 34
	s_mul_hi_u32 s4, s2, s10
	s_mul_i32 s4, s4, s93
	s_sub_i32 s2, s2, s4
	s_sub_i32 s4, s2, s93
	s_cmp_ge_u32 s2, s93
	s_cselect_b32 s2, s4, s2
	s_sub_i32 s4, s2, s93
	s_cmp_ge_u32 s2, s93
	s_cselect_b32 s2, s4, s2
	s_xor_b32 s2, s2, s1
	s_sub_i32 s1, s1, s2
	s_add_i32 s0, s0, s1
	s_cmp_lt_i32 s82, s0
	v_writelane_b32 v254, s0, 35
	s_cselect_b64 s[0:1], -1, 0
	v_writelane_b32 v254, s0, 36
	v_and_b32_e32 v0, 64, v218
	s_movk_i32 s69, 0x7fff
	v_writelane_b32 v254, s1, 37
	s_abs_i32 s1, s3
	s_mul_hi_u32 s2, s1, s10
	s_mul_i32 s2, s2, s93
	s_sub_i32 s1, s1, s2
	s_ashr_i32 s0, s3, 31
	s_sub_i32 s2, s1, s93
	s_cmp_ge_u32 s1, s93
	s_cselect_b32 s1, s2, s1
	s_sub_i32 s2, s1, s93
	s_cmp_ge_u32 s1, s93
	s_cselect_b32 s1, s2, s1
	s_xor_b32 s1, s1, s0
	s_sub_i32 s0, s0, s1
	s_add_i32 s0, s3, s0
	v_writelane_b32 v254, s10, 38
	s_cmp_lt_i32 s82, s0
	v_writelane_b32 v254, s0, 39
	s_cselect_b64 s[0:1], -1, 0
	v_writelane_b32 v254, s0, 40
	s_lshl_b32 s68, s33, 6
	s_mov_b64 s[2:3], -1
	v_writelane_b32 v254, s1, 41
	v_writelane_b32 v254, s11, 42
	s_lshl_b32 s0, s11, 6
	v_writelane_b32 v254, s0, 43
	v_writelane_b32 v254, s12, 44
	s_lshl_b32 s0, s12, 6
	v_writelane_b32 v254, s0, 45
	v_writelane_b32 v254, s13, 46
	s_lshl_b32 s0, s13, 6
	v_writelane_b32 v254, s0, 47
	v_writelane_b32 v254, s9, 48
	s_lshl_b32 s0, s9, 6
	v_writelane_b32 v254, s0, 49
	s_add_u32 s0, s48, 0x4000
	s_addc_u32 s1, s49, 0
	v_writelane_b32 v254, s0, 50
	s_movk_i32 s76, 0x447f
	s_movk_i32 s74, 0x5800
	v_writelane_b32 v254, s1, 51
	s_add_u32 s0, s48, 0x8000
	s_addc_u32 s1, s49, 0
	v_writelane_b32 v254, s0, 52
	s_movk_i32 s72, 0x90
	s_mov_b32 s73, 0xfffffc0
	v_writelane_b32 v254, s1, 53
	s_add_u32 s0, s52, 0x1c00
	v_writelane_b32 v254, s0, 54
	s_addc_u32 s0, s53, 0
	v_writelane_b32 v254, s0, 55
	s_add_u32 s0, s50, 0xe629600
	s_addc_u32 s1, s51, 0
	v_writelane_b32 v254, s0, 56
	s_movk_i32 s71, 0x1200
	s_mov_b32 s70, 0x42b17217
	v_writelane_b32 v254, s1, 57
	s_add_u32 s0, s50, 0x110f9e00
	v_writelane_b32 v254, s0, 58
	s_addc_u32 s0, s51, 0
	v_writelane_b32 v254, s0, 59
	v_writelane_b32 v254, s4, 60
	s_mov_b64 s[0:1], 0x100
	v_add_u32_e32 v219, 64, v0
	v_writelane_b32 v254, s5, 61
	v_xor_b32_e32 v227, 32, v218
	v_writelane_b32 v254, s4, 62
	v_xor_b32_e32 v225, 16, v218
	v_xor_b32_e32 v223, 8, v218
	v_writelane_b32 v254, s5, 63
	v_xor_b32_e32 v222, 4, v218
	v_writelane_b32 v255, s4, 0
	v_xor_b32_e32 v221, 2, v218
	v_xor_b32_e32 v220, 1, v218
	v_writelane_b32 v255, s5, 1
	v_mov_b32_e32 v237, 0xff800000
	v_writelane_b32 v255, s4, 2
	v_mov_b32_e32 v238, 0x7f000000
	v_mov_b32_e32 v202, 0x3f317218
	v_writelane_b32 v255, s5, 3
	v_mov_b32_e32 v239, 0x4400
	v_writelane_b32 v255, s4, 4
	v_mov_b32_e32 v240, 0x3000
	v_mov_b32_e32 v241, 0x8900
	v_writelane_b32 v255, s5, 5
	v_mov_b32_e32 v242, 0x1200
	v_writelane_b32 v255, s4, 6
	v_mov_b32_e32 v243, 0x2080
	v_mov_b32_e32 v244, 0x4000
	v_writelane_b32 v255, s5, 7
	s_mov_b32 s8, s95
	v_writelane_b32 v255, s4, 8
	v_readlane_b32 s54, v252, 2
	v_readlane_b32 s55, v252, 3
	v_writelane_b32 v255, s5, 9
	v_readlane_b32 s56, v252, 4
	v_writelane_b32 v255, s4, 10
	v_readlane_b32 s57, v252, 5
	v_readlane_b32 s58, v252, 6
	v_writelane_b32 v255, s5, 11
	v_readlane_b32 s59, v252, 7
	v_writelane_b32 v255, s4, 12
	v_readlane_b32 s60, v252, 8
	v_readlane_b32 s61, v252, 9
	v_writelane_b32 v255, s5, 13
	v_writelane_b32 v255, s82, 14
	v_writelane_b32 v255, s81, 15
	v_readlane_b32 s62, v252, 10
	v_readlane_b32 s63, v252, 11
	v_readlane_b32 s64, v252, 12
	v_readlane_b32 s65, v252, 13
	v_readlane_b32 s66, v252, 14
	v_readlane_b32 s67, v252, 15
	s_branch .LBB0_3

.LBB0_134:
	s_mov_b64 s[2:3], 0
	v_readlane_b32 s81, v255, 15
	v_readlane_b32 s82, v255, 14
	s_cmp_eq_u32 s101, 0
	s_cbranch_scc1 .LBB0_135
	s_waitcnt vmcnt(0) lgkmcnt(0)
	s_barrier
	s_mov_b64 s[2:3], exec
	v_readlane_b32 s4, v253, 30
	v_readlane_b32 s5, v253, 31
	s_nop 0
	s_and_b64 s[4:5], s[2:3], s[4:5]
	s_mov_b64 exec, s[4:5]
	s_cbranch_execz .Lmx_sigdone
	buffer_wbl2 sc1
	v_readlane_b32 s8, v255, 28
	v_readlane_b32 s9, v255, 29
	v_mov_b32_e32 v1, 1
	s_lshl_b32 s4, s101, 2
	s_add_u32 s4, s4, 60
	s_add_u32 s8, s8, s4
	s_addc_u32 s9, s9, 0
	s_waitcnt vmcnt(0)
	global_atomic_add v201, v1, s[8:9]
.Lmx_sigdone:
	s_or_b64 exec, exec, s[2:3]
	s_mov_b32 s101, 0
	s_branch .LBB0_527

.LBB0_140:
	s_or_b64 exec, exec, s[2:3]
	s_waitcnt lgkmcnt(0)
	s_barrier
	s_waitcnt vmcnt(0)
	ds_read_b32 v0, v201 offset:64512
	s_movk_i32 s2, 0x69f
	s_waitcnt lgkmcnt(0)
	v_add_u32_e32 v0, 0x80, v0
	s_nop 0
	v_cmp_lt_i32_e32 vcc, s2, v0
	v_readfirstlane_b32 s31, v0
	s_mov_b64 s[2:3], -1
	s_cbranch_vccnz .LBB0_135
.Lmx_disp1:
	v_readlane_b32 s2, v255, 18
	v_readlane_b32 s3, v255, 19
	s_mov_b32 s92, s2
	s_cmpk_gt_i32 s31, 0x7f
	s_mov_b64 s[2:3], -1
	s_cbranch_scc0 .LBB0_445
	s_cmpk_gt_u32 s31, 0x69f
	s_cbranch_scc0 .LBB0_251
	s_cmpk_gt_u32 s31, 0x8a7
	s_cbranch_scc0 .LBB0_173
	s_cmpk_gt_u32 s31, 0x927
	s_cbranch_scc0 .LBB0_168
	v_mov_b32_e32 v40, v216
	s_lshl_b32 s4, s92, 4
	v_readfirstlane_b32 s2, v40
	s_ashr_i32 s3, s2, 6
	s_lshl_b32 s2, s31, 2
	s_and_b32 s2, s2, 12
	s_add_i32 s2, s3, s2
	s_add_i32 s4, s2, s4
	s_ashr_i32 s5, s4, 31
	v_readlane_b32 s52, v252, 16
	s_lshl_b64 s[8:9], s[4:5], 2
	v_readlane_b32 s62, v252, 26
	v_readlane_b32 s63, v252, 27
	s_add_u32 s8, s62, s8
	s_addc_u32 s9, s63, s9
	global_load_dword v4, v201, s[8:9]
	s_waitcnt vmcnt(39)
	v_and_b32_e32 v72, 63, v40
	v_lshl_or_b32 v0, s4, 6, v72
	v_ashrrev_i32_e32 v1, 31, v0
	v_readlane_b32 s60, v252, 24
	v_readlane_b32 s61, v252, 25
	v_lshlrev_b64 v[0:1], 2, v[0:1]
	v_readlane_b32 s58, v252, 22
	v_lshl_add_u64 v[2:3], s[60:61], 0, v[0:1]
	global_load_dword v37, v[2:3], off
	v_readlane_b32 s59, v252, 23
	s_mov_b32 s8, 0x3fb8aa3b
	v_readlane_b32 s53, v252, 17
	v_lshl_add_u64 v[0:1], s[58:59], 0, v[0:1]
	global_load_dword v39, v[0:1], off
	v_readlane_b32 s54, v252, 18
	v_readlane_b32 s55, v252, 19
	v_readlane_b32 s56, v252, 20
	v_readlane_b32 s57, v252, 21
	v_readlane_b32 s64, v252, 28
	v_readlane_b32 s65, v252, 29
	v_readlane_b32 s66, v252, 30
	v_readlane_b32 s67, v252, 31
	s_waitcnt vmcnt(2)
	v_mul_f32_e32 v0, 0x3fb8aa3b, v4
	v_fma_f32 v1, v4, s8, -v0
	v_rndne_f32_e32 v2, v0
	v_fmac_f32_e32 v1, 0x32a5705f, v4
	v_sub_f32_e32 v0, v0, v2
	v_add_f32_e32 v0, v0, v1
	v_cvt_i32_f32_e32 v2, v2
	v_exp_f32_e32 v0, v0
	s_mov_b32 s8, 0xc2ce8ed0
	v_cmp_ngt_f32_e32 vcc, s8, v4
	s_mov_b32 s8, 0x42b17218
	v_ldexp_f32 v0, v0, v2
	v_cndmask_b32_e32 v0, 0, v0, vcc
	v_cmp_nlt_f32_e32 vcc, s8, v4
	s_brev_b32 s8, 18
	s_nop 0
	v_cndmask_b32_e32 v41, v233, v0, vcc
	s_waitcnt vmcnt(1)
	v_mul_f32_e32 v36, v37, v41
	v_and_b32_e32 v38, 0x7fffffff, v36
	v_lshrrev_b32_e32 v0, 23, v38
	v_and_b32_e32 v2, 0x7fffff, v38
	v_cmp_nlt_f32_e64 s[14:15], |v36|, s8
	v_add_u32_e32 v1, 0xffffff88, v0
	v_or_b32_e32 v0, 0x800000, v2
	s_and_saveexec_b64 s[8:9], s[14:15]
	s_xor_b64 s[16:17], exec, s[8:9]
	s_cbranch_execz .LBB0_147
	v_cmp_lt_u32_e32 vcc, 63, v1
	s_mov_b32 s12, 0xfe5163ab
	s_nop 0
	v_cndmask_b32_e32 v2, 0, v234, vcc
	v_add_u32_e32 v2, v2, v1
	v_cmp_lt_u32_e64 s[8:9], 31, v2
	s_nop 1
	v_cndmask_b32_e64 v3, 0, v235, s[8:9]
	v_add_u32_e32 v2, v3, v2
	v_cmp_lt_u32_e64 s[10:11], 31, v2
	s_nop 1
	v_cndmask_b32_e64 v3, 0, v235, s[10:11]
	v_add_u32_e32 v16, v3, v2
	v_mad_u64_u32 v[2:3], s[12:13], v0, s12, 0
	v_mov_b32_e32 v200, v3
	s_mov_b32 s12, 0x3c439041
	v_mad_u64_u32 v[4:5], s[12:13], v0, s12, v[200:201]
	v_mov_b32_e32 v200, v5
	s_mov_b32 s12, 0xdb629599
	v_mad_u64_u32 v[6:7], s[12:13], v0, s12, v[200:201]
	v_mov_b32_e32 v200, v7
	s_mov_b32 s12, 0xf534ddc0
	v_mad_u64_u32 v[8:9], s[12:13], v0, s12, v[200:201]
	v_mov_b32_e32 v200, v9
	s_mov_b32 s12, 0xfc2757d1
	v_mad_u64_u32 v[10:11], s[12:13], v0, s12, v[200:201]
	v_mov_b32_e32 v200, v11
	s_mov_b32 s12, 0x4e441529
	v_mad_u64_u32 v[12:13], s[12:13], v0, s12, v[200:201]
	v_mov_b32_e32 v200, v13
	s_mov_b32 s12, 0xa2f9836e
	v_mad_u64_u32 v[14:15], s[12:13], v0, s12, v[200:201]
	v_cndmask_b32_e32 v3, v12, v8, vcc
	v_cndmask_b32_e32 v5, v14, v10, vcc
	v_cndmask_b32_e32 v9, v15, v12, vcc
	v_cndmask_b32_e64 v7, v5, v3, s[8:9]
	v_cndmask_b32_e64 v5, v9, v5, s[8:9]
	v_cndmask_b32_e32 v9, v10, v6, vcc
	v_cndmask_b32_e64 v3, v3, v9, s[8:9]
	v_cndmask_b32_e32 v4, v8, v4, vcc
	v_cndmask_b32_e64 v5, v5, v7, s[10:11]
	v_cndmask_b32_e64 v7, v7, v3, s[10:11]
	v_sub_u32_e32 v10, 32, v16
	v_cndmask_b32_e64 v8, v9, v4, s[8:9]
	v_alignbit_b32 v11, v5, v7, v10
	v_cmp_eq_u32_e64 s[12:13], 0, v16
	v_cndmask_b32_e64 v3, v3, v8, s[10:11]
	v_alignbit_b32 v9, v7, v3, v10
	v_cndmask_b32_e64 v5, v11, v5, s[12:13]
	v_cndmask_b32_e32 v2, v6, v2, vcc
	v_cndmask_b32_e64 v7, v9, v7, s[12:13]
	v_bfe_u32 v12, v5, 29, 1
	v_cndmask_b32_e64 v2, v4, v2, s[8:9]
	v_alignbit_b32 v9, v5, v7, 30
	v_sub_u32_e32 v13, 0, v12
	v_cndmask_b32_e64 v2, v8, v2, s[10:11]
	v_xor_b32_e32 v9, v9, v13
	v_alignbit_b32 v4, v3, v2, v10
	v_cndmask_b32_e64 v3, v4, v3, s[12:13]
	v_ffbh_u32_e32 v6, v9
	v_alignbit_b32 v4, v7, v3, 30
	v_min_u32_e32 v6, 32, v6
	v_alignbit_b32 v2, v3, v2, 30
	v_xor_b32_e32 v4, v4, v13
	v_sub_u32_e32 v7, 31, v6
	v_xor_b32_e32 v2, v2, v13
	v_alignbit_b32 v8, v9, v4, v7
	v_alignbit_b32 v2, v4, v2, v7
	v_alignbit_b32 v3, v8, v2, 9
	v_ffbh_u32_e32 v4, v3
	v_min_u32_e32 v4, 32, v4
	v_lshrrev_b32_e32 v11, 29, v5
	v_not_b32_e32 v7, v4
	v_alignbit_b32 v2, v3, v2, v7
	v_lshlrev_b32_e32 v3, 31, v11
	v_or_b32_e32 v7, 0x33000000, v3
	v_add_lshl_u32 v4, v4, v6, 23
	v_lshrrev_b32_e32 v2, 9, v2
	v_sub_u32_e32 v4, v7, v4
	v_or_b32_e32 v3, 0.5, v3
	v_lshlrev_b32_e32 v6, 23, v6
	v_or_b32_e32 v2, v4, v2
	v_lshrrev_b32_e32 v4, 9, v8
	v_sub_u32_e32 v3, v3, v6
	v_or_b32_e32 v3, v4, v3
	v_mul_f32_e32 v4, 0x3fc90fda, v3
	s_mov_b32 s8, 0x3fc90fda
	v_fma_f32 v6, v3, s8, -v4
	v_fmac_f32_e32 v6, 0x33a22168, v3
	v_fmac_f32_e32 v6, 0x3fc90fda, v2
	v_lshrrev_b32_e32 v2, 30, v5
	v_add_f32_e32 v43, v4, v6
	v_add_u32_e32 v42, v12, v2

.LBB0_533:
	s_or_b64 exec, exec, s[2:3]
	s_waitcnt lgkmcnt(0)
	s_barrier
	s_waitcnt vmcnt(0)
	ds_read_b32 v0, v201 offset:64512
	s_movk_i32 s2, 0xc73
	s_waitcnt lgkmcnt(0)
	v_cmp_lt_i32_e32 vcc, s2, v0
	v_readfirstlane_b32 s21, v0
	s_mov_b64 s[2:3], -1
	s_cbranch_vccnz .LBB0_528
	s_cmp_lt_u32 s21, 32
	s_cbranch_scc1 .Lmx_go2
	s_cmp_lt_u32 s21, 160
	s_cbranch_scc0 .Lmx_a
	s_sub_u32 s31, s21, 32
	s_mov_b32 s101, 1
	s_branch .Lmx_disp1
.Lmx_a:
	s_cmp_lt_u32 s21, 1320
	s_cbranch_scc0 .Lmx_c
	s_add_u32 s31, s21, 1536
	s_mov_b32 s101, 2
	s_cmp_lt_u32 s21, 808
	s_cbranch_scc1 .Lmx_disp1
	s_mov_b32 s101, 1
	s_branch .Lmx_disp1
.Lmx_c:
	s_cmp_lt_u32 s21, 1968
	s_cbranch_scc0 .Lmx_d
	s_sub_u32 s21, s21, 68
	s_branch .Lmx_go2
.Lmx_d:
	s_cmp_lt_u32 s21, 2480
	s_cbranch_scc0 .Lmx_e
	s_sub_u32 s21, s21, 1356
	s_branch .Lmx_go2
.Lmx_e:
	s_cmp_lt_u32 s21, 2512
	s_cbranch_scc0 .Lmx_f
	s_sub_u32 s21, s21, 2448
	s_branch .Lmx_waitC2
.Lmx_f:
	s_cmp_lt_u32 s21, 2640
	s_cbranch_scc0 .Lmx_g
	s_sub_u32 s21, s21, 1388
.Lmx_waitC2:
	s_movk_i32 s5, 68
	s_movk_i32 s10, 648
	s_branch .Lmx_wait
.Lmx_g:
	s_sub_u32 s21, s21, 2576
	s_movk_i32 s5, 64
	s_movk_i32 s10, 640
.Lmx_wait:
	v_readfirstlane_b32 s4, v216
	v_readlane_b32 s8, v255, 28
	v_readlane_b32 s9, v255, 29
	s_nop 0
	s_add_u32 s8, s8, s5
	s_addc_u32 s9, s9, 0
	s_cmp_lt_u32 s4, 64
	s_cbranch_scc0 .Lmx_wjoin
.Lmx_wloop:
	global_load_dword v0, v201, s[8:9] sc1
	s_waitcnt vmcnt(0)
	v_readfirstlane_b32 s4, v0
	s_nop 0
	s_cmp_ge_u32 s4, s10
	s_cbranch_scc1 .Lmx_wjoin
	s_sleep 127
	s_branch .Lmx_wloop
.Lmx_wjoin:
	s_barrier
	buffer_inv sc1
	s_waitcnt vmcnt(0)
.Lmx_go2:
	v_mov_b32_e32 v0, s21
	v_readlane_b32 s2, v255, 18
	v_readlane_b32 s3, v255, 19
	s_mov_b32 s20, s2
	s_cmp_gt_i32 s21, 31
	s_mov_b64 s[2:3], -1
	s_cbranch_scc0 .LBB0_758
	s_cmp_gt_u32 s21, 63
	s_cbranch_scc0 .LBB0_707
	s_cmpk_gt_u32 s21, 0x263
	s_cbranch_scc0 .LBB0_704
	s_cmpk_gt_u32 s21, 0x463
	s_cbranch_scc0 .LBB0_657
	s_cmpk_gt_u32 s21, 0x4e3
	s_cbranch_scc0 .LBB0_622
	s_mov_b64 s[4:5], -1
	s_cmpk_gt_u32 s21, 0x6eb
	s_mul_i32 s2, s20, 31
	s_cbranch_scc0 .LBB0_582
	s_lshl_b32 s3, s20, 7
	s_add_i32 s3, s21, s3
	s_add_i32 s4, s3, 0xfffff914
	s_lshl_b32 s10, s21, 3
	s_mul_hi_i32 s3, s4, 0x7800
	s_mul_i32 s11, s4, 0x7800
	v_readlane_b32 s4, v254, 54
	v_mov_b32_e32 v8, v216
	s_add_u32 s4, s4, s11
	v_readlane_b32 s5, v254, 55
	s_addc_u32 s5, s5, s3
	v_lshlrev_b32_e32 v66, 2, v8
	v_ashrrev_i32_e32 v9, 31, v8
	v_lshl_add_u64 v[0:1], v[8:9], 2, s[4:5]
	s_mov_b32 s12, 0
	v_mov_b32_e32 v2, v66
	s_branch .LBB0_543
